# LDS bank-conflict swizzle: importance-table columns XOR-swizzled by row (pass-2 writes 16-way -> 2-way conflicts; top-k reads un-permute per row)
# speedup vs baseline: 1.0127x; 1.0073x over previous
.LBB0_364:
	v_and_b32_e32 v20, 64, v147
	s_lshl_b32 s4, s25, 3
	v_readlane_b32 s5, v255, 21
	v_xor_b32_e32 v0, 16, v147
	v_add_u32_e32 v38, 64, v20
	s_add_i32 s4, s4, s5
	v_cmp_lt_i32_e32 vcc, v0, v38
	s_ashr_i32 s5, s4, 31
	s_lshl_b64 s[4:5], s[4:5], 13
	v_cndmask_b32_e32 v0, v147, v0, vcc
	v_lshlrev_b32_e32 v119, 2, v0
	v_xor_b32_e32 v0, 32, v147
	v_lshl_add_u64 v[116:117], v[124:125], 0, s[4:5]
	v_cmp_lt_i32_e32 vcc, v0, v38
	s_add_i32 s5, s2, s22
	v_or_b32_e32 v114, s5, v122
	v_cndmask_b32_e32 v0, v147, v0, vcc
	v_mul_u32_u24_e32 v118, 3, v145
	v_readlane_b32 s6, v255, 18
	v_lshlrev_b32_e32 v137, 2, v0
	v_lshlrev_b32_e32 v0, 1, v118
	v_readlane_b32 s7, v255, 19
	v_ashrrev_i32_e32 v115, 31, v114
	v_lshlrev_b64 v[120:121], 13, v[114:115]
	v_lshl_add_u64 v[18:19], s[6:7], 0, v[0:1]
	v_lshl_add_u64 v[24:25], v[18:19], 0, v[120:121]
	s_movk_i32 s5, 0x1000
	v_add_co_u32_e32 v24, vcc, s5, v24
	ds_bpermute_b32 v22, v119, v188
	s_nop 0
	v_addc_co_u32_e32 v25, vcc, 0, v25, vcc
	global_load_ushort v0, v[24:25], off offset:3584
	s_mov_b64 s[98:99], 0x8000
	v_lshl_add_u64 v[56:57], v[24:25], 0, s[98:99]
	global_load_ushort v58, v[56:57], off offset:3584
	s_mov_b32 s4, 0
	s_movk_i32 s83, 0x1000
	v_sub_u32_e32 v40, v225, v143
	v_add_u32_e32 v41, s14, v228
	v_mov_b32_e32 v42, v227
	v_mov_b32_e32 v43, v223
	v_mov_b32_e32 v44, v222
	v_mov_b32_e32 v45, v226
	v_mov_b32_e32 v31, 0
	s_waitcnt vmcnt(0)
	v_lshlrev_b32_e32 v0, 16, v0
	v_mul_f32_e32 v0, 0xbfb8aa3b, v0
	v_exp_f32_e32 v0, v0
	s_nop 0
	v_add_f32_e32 v0, 1.0, v0
	v_div_scale_f32 v21, s[6:7], v0, v0, 1.0
	v_rcp_f32_e32 v23, v21
	s_nop 0
	v_fma_f32 v24, -v21, v23, 1.0
	v_fmac_f32_e32 v23, v24, v23
	v_div_scale_f32 v24, vcc, 1.0, v0, 1.0
	v_mul_f32_e32 v25, v24, v23
	v_fma_f32 v26, -v21, v25, v24
	v_fmac_f32_e32 v25, v26, v23
	v_fma_f32 v21, -v21, v25, v24
	v_div_fmas_f32 v21, v21, v23, v25
	ds_bpermute_b32 v23, v119, v189
	v_div_fixup_f32 v0, v21, v0, 1.0
	s_waitcnt lgkmcnt(0)
	v_pk_add_f32 v[22:23], v[188:189], v[22:23]
	ds_bpermute_b32 v24, v137, v22
	ds_bpermute_b32 v25, v137, v23
	s_waitcnt lgkmcnt(0)
	v_pk_add_f32 v[28:29], v[22:23], v[24:25]
	s_nop 0
	v_div_scale_f32 v21, s[6:7], v28, v28, 1.0
	v_rcp_f32_e32 v22, v21
	v_cmp_lt_f32_e64 s[42:43], 0, v29
	v_fma_f32 v23, -v21, v22, 1.0
	v_fmac_f32_e32 v22, v23, v22
	v_div_scale_f32 v23, vcc, 1.0, v28, 1.0
	v_mul_f32_e32 v24, v23, v22
	v_fma_f32 v25, -v21, v24, v23
	v_fmac_f32_e32 v24, v25, v22
	v_fma_f32 v21, -v21, v24, v23
	v_div_fmas_f32 v21, v21, v22, v24
	v_div_fixup_f32 v21, v21, v28, 1.0
	v_cmp_lt_f32_e32 vcc, 0, v28
	v_mov_b32_e32 v23, 0
	s_nop 0
	v_cndmask_b32_e32 v34, 0, v21, vcc
	v_mul_f32_e32 v0, v34, v0
	v_pk_mul_f32 v[26:27], v[100:101], v[0:1] op_sel_hi:[1,0]
	v_pk_mul_f32 v[24:25], v[98:99], v[0:1] op_sel_hi:[1,0]
	global_store_dwordx4 v[116:117], v[24:27], off
	v_mov_b32_e32 v35, v34
	s_nop 0
	v_pk_mul_f32 v[26:27], v[104:105], v[0:1] op_sel_hi:[1,0]
	v_pk_mul_f32 v[24:25], v[102:103], v[0:1] op_sel_hi:[1,0]
	global_store_dwordx4 v[116:117], v[24:27], off offset:1024
	v_or_b32_e32 v102, 4, v114
	v_ashrrev_i32_e32 v103, 31, v102
	v_pk_mul_f32 v[26:27], v[108:109], v[0:1] op_sel_hi:[1,0]
	v_pk_mul_f32 v[24:25], v[106:107], v[0:1] op_sel_hi:[1,0]
	global_store_dwordx4 v[116:117], v[24:27], off offset:2048
	s_nop 1
	v_pk_mul_f32 v[26:27], v[112:113], v[0:1] op_sel_hi:[1,0]
	v_pk_mul_f32 v[24:25], v[110:111], v[0:1] op_sel_hi:[1,0]
	v_div_scale_f32 v0, s[6:7], v29, v29, 1.0
	v_rcp_f32_e32 v21, v0
	global_store_dwordx4 v[116:117], v[24:27], off offset:3072
	v_lshlrev_b64 v[112:113], 13, v[102:103]
	v_lshl_add_u64 v[18:19], v[18:19], 0, v[112:113]
	v_fma_f32 v22, -v0, v21, 1.0
	v_fmac_f32_e32 v21, v22, v21
	v_div_scale_f32 v22, vcc, 1.0, v29, 1.0
	v_mul_f32_e32 v24, v22, v21
	v_fma_f32 v25, -v0, v24, v22
	v_fmac_f32_e32 v24, v25, v21
	v_fma_f32 v0, -v0, v24, v22
	v_div_fmas_f32 v0, v0, v21, v24
	v_add_co_u32_e32 v18, vcc, s5, v18
	v_div_fixup_f32 v0, v0, v29, 1.0
	s_nop 0
	v_addc_co_u32_e32 v19, vcc, 0, v19, vcc
	v_cndmask_b32_e64 v36, 0, v0, s[42:43]
	v_mov_b32_e32 v0, v58
	v_mov_b32_e32 v37, v36
	v_lshlrev_b32_e32 v0, 16, v0
	v_mul_f32_e32 v0, 0xbfb8aa3b, v0
	v_exp_f32_e32 v0, v0
	s_nop 0
	v_add_f32_e32 v0, 1.0, v0
	v_div_scale_f32 v18, s[6:7], v0, v0, 1.0
	v_rcp_f32_e32 v19, v18
	s_mov_b64 s[6:7], 0x1000
	v_lshl_add_u64 v[110:111], v[116:117], 0, s[6:7]
	s_mov_b64 s[6:7], 0x1400
	v_fma_f32 v21, -v18, v19, 1.0
	v_fmac_f32_e32 v19, v21, v19
	v_div_scale_f32 v21, vcc, 1.0, v0, 1.0
	v_mul_f32_e32 v22, v21, v19
	v_fma_f32 v24, -v18, v22, v21
	v_fmac_f32_e32 v22, v24, v19
	v_fma_f32 v18, -v18, v22, v21
	v_div_fmas_f32 v18, v18, v19, v22
	v_div_fixup_f32 v0, v18, v0, 1.0
	v_mul_f32_e32 v0, v36, v0
	v_add_co_u32_e32 v18, vcc, s5, v116
	v_pk_mul_f32 v[26:27], v[84:85], v[0:1] op_sel_hi:[1,0]
	v_pk_mul_f32 v[24:25], v[82:83], v[0:1] op_sel_hi:[1,0]
	v_addc_co_u32_e32 v19, vcc, 0, v117, vcc
	global_store_dwordx4 v[18:19], v[24:27], off
	v_lshl_add_u64 v[106:107], v[116:117], 0, s[6:7]
	s_mov_b64 s[6:7], 0x1800
	v_pk_mul_f32 v[26:27], v[88:89], v[0:1] op_sel_hi:[1,0]
	v_pk_mul_f32 v[24:25], v[86:87], v[0:1] op_sel_hi:[1,0]
	global_store_dwordx4 v[18:19], v[24:27], off offset:1024
	v_lshl_add_u64 v[108:109], v[116:117], 0, s[6:7]
	s_mov_b64 s[6:7], 0x1c00
	v_pk_mul_f32 v[26:27], v[92:93], v[0:1] op_sel_hi:[1,0]
	v_pk_mul_f32 v[24:25], v[90:91], v[0:1] op_sel_hi:[1,0]
	global_store_dwordx4 v[18:19], v[24:27], off offset:2048
	v_lshl_add_u64 v[104:105], v[116:117], 0, s[6:7]
	s_lshl_b32 s6, s0, 8
	v_pk_mul_f32 v[26:27], v[96:97], v[0:1] op_sel_hi:[1,0]
	v_pk_mul_f32 v[24:25], v[94:95], v[0:1] op_sel_hi:[1,0]
	v_or_b32_e32 v0, v20, v210
	v_lshlrev_b32_e32 v0, 2, v0
	s_add_i32 s5, s2, 0xfffffbe8
	v_subrev_u32_e32 v39, s6, v224
	global_store_dwordx4 v[18:19], v[24:27], off offset:3072
	s_barrier
	v_and_b32_e32 v141, 15, v146
	v_lshlrev_b32_e32 v141, 4, v141
	s_branch .LBB0_366

.Lp2k:
	s_andn2_b64 vcc, exec, s[8:9]
	s_cbranch_vccnz .Lp2k_inv
	s_cmp_lt_i32 s10, 1
	s_cbranch_scc1 .Lp2k_p0
	s_cmp_lg_u32 s10, 1
	s_cbranch_scc0 .Lp2k_p1
	ds_read_b128 v[56:59], v47
	ds_read_b128 v[64:67], v48
	ds_read_b128 v[60:63], v47 offset:2048
	ds_read_b128 v[68:71], v48 offset:2048
	ds_read_b32 v96, v193
	s_waitcnt lgkmcnt(1)
	v_mfma_f32_16x16x32_bf16 v[72:75], v[56:59], v[2:5], 0
	v_mfma_f32_16x16x32_bf16 v[76:79], v[60:63], v[2:5], 0
	v_mfma_f32_16x16x32_bf16 v[72:75], v[64:67], v[6:9], v[72:75]
	v_mfma_f32_16x16x32_bf16 v[76:79], v[68:71], v[6:9], v[76:79]
	v_mfma_f32_16x16x32_bf16 v[56:59], v[56:59], v[10:13], 0
	v_mfma_f32_16x16x32_bf16 v[60:63], v[60:63], v[10:13], 0
	v_mfma_f32_16x16x32_bf16 v[56:59], v[64:67], v[14:17], v[56:59]
	v_mfma_f32_16x16x32_bf16 v[60:63], v[68:71], v[14:17], v[60:63]
	s_waitcnt lgkmcnt(0)
	s_nop 7
	v_pk_fma_f32 v[80:81], v[72:73], s[36:37], v[96:97] op_sel_hi:[1,0,0]
	v_pk_fma_f32 v[82:83], v[74:75], s[36:37], v[96:97] op_sel_hi:[1,0,0]
	v_pk_fma_f32 v[84:85], v[76:77], s[36:37], v[96:97] op_sel_hi:[1,0,0]
	v_pk_fma_f32 v[86:87], v[78:79], s[36:37], v[96:97] op_sel_hi:[1,0,0]
	s_nop 0
	v_sub_f32_e32 v80, v80, v161
	v_sub_f32_e32 v81, v81, v161
	v_sub_f32_e32 v82, v82, v161
	v_sub_f32_e32 v83, v83, v161
	v_sub_f32_e32 v84, v84, v161
	v_sub_f32_e32 v85, v85, v161
	v_sub_f32_e32 v86, v86, v161
	v_sub_f32_e32 v87, v87, v161
	v_exp_f32_e32 v80, v80
	v_exp_f32_e32 v81, v81
	v_exp_f32_e32 v82, v82
	v_exp_f32_e32 v83, v83
	v_exp_f32_e32 v84, v84
	v_exp_f32_e32 v85, v85
	v_exp_f32_e32 v86, v86
	v_exp_f32_e32 v87, v87
	s_nop 0
	v_pk_fma_f32 v[88:89], v[56:57], s[36:37], v[96:97] op_sel_hi:[1,0,0]
	v_pk_fma_f32 v[90:91], v[58:59], s[36:37], v[96:97] op_sel_hi:[1,0,0]
	v_pk_fma_f32 v[92:93], v[60:61], s[36:37], v[96:97] op_sel_hi:[1,0,0]
	v_pk_fma_f32 v[94:95], v[62:63], s[36:37], v[96:97] op_sel_hi:[1,0,0]
	s_nop 0
	v_sub_f32_e32 v88, v88, v241
	v_sub_f32_e32 v89, v89, v241
	v_sub_f32_e32 v90, v90, v241
	v_sub_f32_e32 v91, v91, v241
	v_sub_f32_e32 v92, v92, v241
	v_sub_f32_e32 v93, v93, v241
	v_sub_f32_e32 v94, v94, v241
	v_sub_f32_e32 v95, v95, v241
	v_exp_f32_e32 v88, v88
	v_exp_f32_e32 v89, v89
	v_exp_f32_e32 v90, v90
	v_exp_f32_e32 v91, v91
	v_exp_f32_e32 v92, v92
	v_exp_f32_e32 v93, v93
	v_exp_f32_e32 v94, v94
	v_exp_f32_e32 v95, v95
	s_nop 0
	v_mov_b32_e32 v54, v81
	v_mov_b32_e32 v55, v83
	v_mov_b32_e32 v81, v82
	v_pk_mul_f32 v[54:55], v[34:35], v[54:55]
	s_nop 0
	v_pk_fma_f32 v[80:81], v[34:35], v[80:81], v[54:55]
	v_mov_b32_e32 v83, v55
	v_add_f32_e32 v72, v80, v81
	v_mov_b32_e32 v54, v85
	v_mov_b32_e32 v55, v87
	v_mov_b32_e32 v85, v86
	v_pk_mul_f32 v[54:55], v[34:35], v[54:55]
	s_nop 0
	v_pk_fma_f32 v[84:85], v[34:35], v[84:85], v[54:55]
	v_mov_b32_e32 v87, v55
	v_add_f32_e32 v73, v84, v85
	v_mov_b32_e32 v54, v89
	v_mov_b32_e32 v55, v91
	v_mov_b32_e32 v89, v90
	v_pk_mul_f32 v[54:55], v[36:37], v[54:55]
	s_nop 0
	v_pk_fma_f32 v[88:89], v[36:37], v[88:89], v[54:55]
	v_mov_b32_e32 v91, v55
	v_add_f32_e32 v74, v88, v89
	v_mov_b32_e32 v54, v93
	v_mov_b32_e32 v55, v95
	v_mov_b32_e32 v93, v94
	v_pk_mul_f32 v[54:55], v[36:37], v[54:55]
	s_nop 0
	v_pk_fma_f32 v[92:93], v[36:37], v[92:93], v[54:55]
	v_mov_b32_e32 v95, v55
	v_add_f32_e32 v75, v92, v93
	v_cndmask_b32_e64 v76, v83, v31, s[38:39]
	v_cndmask_b32_e64 v77, v87, v83, s[38:39]
	v_cndmask_b32_e64 v78, v91, v23, s[38:39]
	v_cndmask_b32_e64 v79, v95, v91, s[38:39]
	ds_bpermute_b32 v76, v0, v76
	ds_bpermute_b32 v77, v0, v77
	ds_bpermute_b32 v78, v0, v78
	ds_bpermute_b32 v79, v0, v79
	v_mov_b32_e32 v31, v87
	v_mov_b32_e32 v23, v95
	v_mov_b32_e32 v54, v49
	v_add_u32_e32 v55, 16, v49
	s_waitcnt lgkmcnt(0)
	v_add_f32_e32 v76, v72, v76
	v_add_f32_e32 v77, v73, v77
	v_add_f32_e32 v78, v74, v78
	v_add_f32_e32 v79, v75, v79
	v_xor_b32_e32 v54, v141, v54
	ds_write2st64_b32 v54, v76, v78 offset1:4
	v_xor_b32_e32 v55, v141, v55
	ds_write2st64_b32 v55, v77, v79 offset1:4
	ds_read_b128 v[56:59], v47 offset:4096
	ds_read_b128 v[64:67], v48 offset:4096
	ds_read_b128 v[60:63], v47 offset:6144
	ds_read_b128 v[68:71], v48 offset:6144
	ds_read_b32 v96, v193
	s_waitcnt lgkmcnt(1)
	v_mfma_f32_16x16x32_bf16 v[72:75], v[56:59], v[2:5], 0
	v_mfma_f32_16x16x32_bf16 v[76:79], v[60:63], v[2:5], 0
	v_mfma_f32_16x16x32_bf16 v[72:75], v[64:67], v[6:9], v[72:75]
	v_mfma_f32_16x16x32_bf16 v[76:79], v[68:71], v[6:9], v[76:79]
	v_mfma_f32_16x16x32_bf16 v[56:59], v[56:59], v[10:13], 0
	v_mfma_f32_16x16x32_bf16 v[60:63], v[60:63], v[10:13], 0
	v_mfma_f32_16x16x32_bf16 v[56:59], v[64:67], v[14:17], v[56:59]
	v_mfma_f32_16x16x32_bf16 v[60:63], v[68:71], v[14:17], v[60:63]
	s_waitcnt lgkmcnt(0)
	s_nop 7
	v_pk_fma_f32 v[80:81], v[72:73], s[36:37], v[96:97] op_sel_hi:[1,0,0]
	v_pk_fma_f32 v[82:83], v[74:75], s[36:37], v[96:97] op_sel_hi:[1,0,0]
	v_pk_fma_f32 v[84:85], v[76:77], s[36:37], v[96:97] op_sel_hi:[1,0,0]
	v_pk_fma_f32 v[86:87], v[78:79], s[36:37], v[96:97] op_sel_hi:[1,0,0]
	s_nop 0
	v_sub_f32_e32 v80, v80, v161
	v_sub_f32_e32 v81, v81, v161
	v_sub_f32_e32 v82, v82, v161
	v_sub_f32_e32 v83, v83, v161
	v_sub_f32_e32 v84, v84, v161
	v_sub_f32_e32 v85, v85, v161
	v_sub_f32_e32 v86, v86, v161
	v_sub_f32_e32 v87, v87, v161
	v_exp_f32_e32 v80, v80
	v_exp_f32_e32 v81, v81
	v_exp_f32_e32 v82, v82
	v_exp_f32_e32 v83, v83
	v_exp_f32_e32 v84, v84
	v_exp_f32_e32 v85, v85
	v_exp_f32_e32 v86, v86
	v_exp_f32_e32 v87, v87
	s_nop 0
	v_pk_fma_f32 v[88:89], v[56:57], s[36:37], v[96:97] op_sel_hi:[1,0,0]
	v_pk_fma_f32 v[90:91], v[58:59], s[36:37], v[96:97] op_sel_hi:[1,0,0]
	v_pk_fma_f32 v[92:93], v[60:61], s[36:37], v[96:97] op_sel_hi:[1,0,0]
	v_pk_fma_f32 v[94:95], v[62:63], s[36:37], v[96:97] op_sel_hi:[1,0,0]
	s_nop 0
	v_sub_f32_e32 v88, v88, v241
	v_sub_f32_e32 v89, v89, v241
	v_sub_f32_e32 v90, v90, v241
	v_sub_f32_e32 v91, v91, v241
	v_sub_f32_e32 v92, v92, v241
	v_sub_f32_e32 v93, v93, v241
	v_sub_f32_e32 v94, v94, v241
	v_sub_f32_e32 v95, v95, v241
	v_exp_f32_e32 v88, v88
	v_exp_f32_e32 v89, v89
	v_exp_f32_e32 v90, v90
	v_exp_f32_e32 v91, v91
	v_exp_f32_e32 v92, v92
	v_exp_f32_e32 v93, v93
	v_exp_f32_e32 v94, v94
	v_exp_f32_e32 v95, v95
	s_nop 0
	v_mov_b32_e32 v54, v81
	v_mov_b32_e32 v55, v83
	v_mov_b32_e32 v81, v82
	v_pk_mul_f32 v[54:55], v[34:35], v[54:55]
	s_nop 0
	v_pk_fma_f32 v[80:81], v[34:35], v[80:81], v[54:55]
	v_mov_b32_e32 v83, v55
	v_add_f32_e32 v72, v80, v81
	v_mov_b32_e32 v54, v85
	v_mov_b32_e32 v55, v87
	v_mov_b32_e32 v85, v86
	v_pk_mul_f32 v[54:55], v[34:35], v[54:55]
	s_nop 0
	v_pk_fma_f32 v[84:85], v[34:35], v[84:85], v[54:55]
	v_mov_b32_e32 v87, v55
	v_add_f32_e32 v73, v84, v85
	v_mov_b32_e32 v54, v89
	v_mov_b32_e32 v55, v91
	v_mov_b32_e32 v89, v90
	v_pk_mul_f32 v[54:55], v[36:37], v[54:55]
	s_nop 0
	v_pk_fma_f32 v[88:89], v[36:37], v[88:89], v[54:55]
	v_mov_b32_e32 v91, v55
	v_add_f32_e32 v74, v88, v89
	v_mov_b32_e32 v54, v93
	v_mov_b32_e32 v55, v95
	v_mov_b32_e32 v93, v94
	v_pk_mul_f32 v[54:55], v[36:37], v[54:55]
	s_nop 0
	v_pk_fma_f32 v[92:93], v[36:37], v[92:93], v[54:55]
	v_mov_b32_e32 v95, v55
	v_add_f32_e32 v75, v92, v93
	v_cndmask_b32_e64 v76, v83, v31, s[38:39]
	v_cndmask_b32_e64 v77, v87, v83, s[38:39]
	v_cndmask_b32_e64 v78, v91, v23, s[38:39]
	v_cndmask_b32_e64 v79, v95, v91, s[38:39]
	ds_bpermute_b32 v76, v0, v76
	ds_bpermute_b32 v77, v0, v77
	ds_bpermute_b32 v78, v0, v78
	ds_bpermute_b32 v79, v0, v79
	v_mov_b32_e32 v31, v87
	v_mov_b32_e32 v23, v95
	v_add_u32_e32 v54, 32, v49
	v_add_u32_e32 v55, 48, v49
	s_waitcnt lgkmcnt(0)
	v_add_f32_e32 v76, v72, v76
	v_add_f32_e32 v77, v73, v77
	v_add_f32_e32 v78, v74, v78
	v_add_f32_e32 v79, v75, v79
	v_xor_b32_e32 v54, v141, v54
	ds_write2st64_b32 v54, v76, v78 offset1:4
	v_xor_b32_e32 v55, v141, v55
	ds_write2st64_b32 v55, v77, v79 offset1:4
	s_branch .LBB0_365
.Lp2k_p1:
	ds_read_b128 v[56:59], v47
	ds_read_b128 v[64:67], v48
	ds_read_b128 v[60:63], v47 offset:2048
	ds_read_b128 v[68:71], v48 offset:2048
	ds_read2_b32 v[80:81], v50 offset1:16
	ds_read2_b32 v[82:83], v50 offset0:32 offset1:48
	v_add_u32_e32 v54, 0x400, v50
	ds_read2_b32 v[84:85], v54 offset1:16
	ds_read2_b32 v[86:87], v54 offset0:32 offset1:48
	ds_read2_b32 v[88:89], v51 offset1:16
	ds_read2_b32 v[90:91], v51 offset0:32 offset1:48
	v_add_u32_e32 v54, 0x400, v51
	ds_read2_b32 v[92:93], v54 offset1:16
	ds_read2_b32 v[94:95], v54 offset0:32 offset1:48
	s_waitcnt lgkmcnt(8)
	v_mfma_f32_16x16x32_bf16 v[72:75], v[56:59], v[2:5], 0
	v_mfma_f32_16x16x32_bf16 v[76:79], v[60:63], v[2:5], 0
	v_mfma_f32_16x16x32_bf16 v[72:75], v[64:67], v[6:9], v[72:75]
	v_mfma_f32_16x16x32_bf16 v[76:79], v[68:71], v[6:9], v[76:79]
	v_mfma_f32_16x16x32_bf16 v[56:59], v[56:59], v[10:13], 0
	v_mfma_f32_16x16x32_bf16 v[60:63], v[60:63], v[10:13], 0
	v_mfma_f32_16x16x32_bf16 v[56:59], v[64:67], v[14:17], v[56:59]
	v_mfma_f32_16x16x32_bf16 v[60:63], v[68:71], v[14:17], v[60:63]
	s_waitcnt lgkmcnt(0)
	s_nop 7
	v_pk_fma_f32 v[80:81], v[72:73], s[36:37], v[80:81] op_sel_hi:[1,0,1]
	v_pk_fma_f32 v[82:83], v[74:75], s[36:37], v[82:83] op_sel_hi:[1,0,1]
	v_pk_fma_f32 v[84:85], v[76:77], s[36:37], v[84:85] op_sel_hi:[1,0,1]
	v_pk_fma_f32 v[86:87], v[78:79], s[36:37], v[86:87] op_sel_hi:[1,0,1]
	s_nop 0
	v_sub_f32_e32 v80, v80, v161
	v_sub_f32_e32 v81, v81, v161
	v_sub_f32_e32 v82, v82, v161
	v_sub_f32_e32 v83, v83, v161
	v_sub_f32_e32 v84, v84, v161
	v_sub_f32_e32 v85, v85, v161
	v_sub_f32_e32 v86, v86, v161
	v_sub_f32_e32 v87, v87, v161
	v_exp_f32_e32 v80, v80
	v_exp_f32_e32 v81, v81
	v_exp_f32_e32 v82, v82
	v_exp_f32_e32 v83, v83
	v_exp_f32_e32 v84, v84
	v_exp_f32_e32 v85, v85
	v_exp_f32_e32 v86, v86
	v_exp_f32_e32 v87, v87
	s_nop 0
	v_pk_fma_f32 v[88:89], v[56:57], s[36:37], v[88:89] op_sel_hi:[1,0,1]
	v_pk_fma_f32 v[90:91], v[58:59], s[36:37], v[90:91] op_sel_hi:[1,0,1]
	v_pk_fma_f32 v[92:93], v[60:61], s[36:37], v[92:93] op_sel_hi:[1,0,1]
	v_pk_fma_f32 v[94:95], v[62:63], s[36:37], v[94:95] op_sel_hi:[1,0,1]
	s_nop 0
	v_sub_f32_e32 v88, v88, v241
	v_sub_f32_e32 v89, v89, v241
	v_sub_f32_e32 v90, v90, v241
	v_sub_f32_e32 v91, v91, v241
	v_sub_f32_e32 v92, v92, v241
	v_sub_f32_e32 v93, v93, v241
	v_sub_f32_e32 v94, v94, v241
	v_sub_f32_e32 v95, v95, v241
	v_exp_f32_e32 v88, v88
	v_exp_f32_e32 v89, v89
	v_exp_f32_e32 v90, v90
	v_exp_f32_e32 v91, v91
	v_exp_f32_e32 v92, v92
	v_exp_f32_e32 v93, v93
	v_exp_f32_e32 v94, v94
	v_exp_f32_e32 v95, v95
	s_nop 0
	v_mov_b32_e32 v54, v81
	v_mov_b32_e32 v55, v83
	v_mov_b32_e32 v81, v82
	v_pk_mul_f32 v[54:55], v[34:35], v[54:55]
	s_nop 0
	v_pk_fma_f32 v[80:81], v[34:35], v[80:81], v[54:55]
	v_mov_b32_e32 v83, v55
	v_add_f32_e32 v72, v80, v81
	v_mov_b32_e32 v54, v85
	v_mov_b32_e32 v55, v87
	v_mov_b32_e32 v85, v86
	v_pk_mul_f32 v[54:55], v[34:35], v[54:55]
	s_nop 0
	v_pk_fma_f32 v[84:85], v[34:35], v[84:85], v[54:55]
	v_mov_b32_e32 v87, v55
	v_add_f32_e32 v73, v84, v85
	v_mov_b32_e32 v54, v89
	v_mov_b32_e32 v55, v91
	v_mov_b32_e32 v89, v90
	v_pk_mul_f32 v[54:55], v[36:37], v[54:55]
	s_nop 0
	v_pk_fma_f32 v[88:89], v[36:37], v[88:89], v[54:55]
	v_mov_b32_e32 v91, v55
	v_add_f32_e32 v74, v88, v89
	v_mov_b32_e32 v54, v93
	v_mov_b32_e32 v55, v95
	v_mov_b32_e32 v93, v94
	v_pk_mul_f32 v[54:55], v[36:37], v[54:55]
	s_nop 0
	v_pk_fma_f32 v[92:93], v[36:37], v[92:93], v[54:55]
	v_mov_b32_e32 v95, v55
	v_add_f32_e32 v75, v92, v93
	v_cndmask_b32_e64 v76, v83, v31, s[38:39]
	v_cndmask_b32_e64 v77, v87, v83, s[38:39]
	v_cndmask_b32_e64 v78, v91, v23, s[38:39]
	v_cndmask_b32_e64 v79, v95, v91, s[38:39]
	ds_bpermute_b32 v76, v0, v76
	ds_bpermute_b32 v77, v0, v77
	ds_bpermute_b32 v78, v0, v78
	ds_bpermute_b32 v79, v0, v79
	v_mov_b32_e32 v31, v87
	v_mov_b32_e32 v23, v95
	v_mov_b32_e32 v54, v49
	v_add_u32_e32 v55, 16, v49
	s_waitcnt lgkmcnt(0)
	v_add_f32_e32 v76, v72, v76
	v_add_f32_e32 v77, v73, v77
	v_add_f32_e32 v78, v74, v78
	v_add_f32_e32 v79, v75, v79
	v_xor_b32_e32 v54, v141, v54
	ds_write2st64_b32 v54, v76, v78 offset1:4
	v_xor_b32_e32 v55, v141, v55
	ds_write2st64_b32 v55, v77, v79 offset1:4
	ds_read_b128 v[56:59], v47 offset:4096
	ds_read_b128 v[64:67], v48 offset:4096
	ds_read_b128 v[60:63], v47 offset:6144
	ds_read_b128 v[68:71], v48 offset:6144
	v_add_u32_e32 v54, 0x800, v50
	ds_read2_b32 v[80:81], v54 offset1:16
	ds_read2_b32 v[82:83], v54 offset0:32 offset1:48
	v_add_u32_e32 v54, 0xc00, v50
	ds_read2_b32 v[84:85], v54 offset1:16
	ds_read2_b32 v[86:87], v54 offset0:32 offset1:48
	v_add_u32_e32 v54, 0x800, v51
	ds_read2_b32 v[88:89], v54 offset1:16
	ds_read2_b32 v[90:91], v54 offset0:32 offset1:48
	v_add_u32_e32 v54, 0xc00, v51
	ds_read2_b32 v[92:93], v54 offset1:16
	ds_read2_b32 v[94:95], v54 offset0:32 offset1:48
	s_waitcnt lgkmcnt(8)
	v_mfma_f32_16x16x32_bf16 v[72:75], v[56:59], v[2:5], 0
	v_mfma_f32_16x16x32_bf16 v[76:79], v[60:63], v[2:5], 0
	v_mfma_f32_16x16x32_bf16 v[72:75], v[64:67], v[6:9], v[72:75]
	v_mfma_f32_16x16x32_bf16 v[76:79], v[68:71], v[6:9], v[76:79]
	v_mfma_f32_16x16x32_bf16 v[56:59], v[56:59], v[10:13], 0
	v_mfma_f32_16x16x32_bf16 v[60:63], v[60:63], v[10:13], 0
	v_mfma_f32_16x16x32_bf16 v[56:59], v[64:67], v[14:17], v[56:59]
	v_mfma_f32_16x16x32_bf16 v[60:63], v[68:71], v[14:17], v[60:63]
	s_waitcnt lgkmcnt(0)
	s_nop 7
	v_pk_fma_f32 v[80:81], v[72:73], s[36:37], v[80:81] op_sel_hi:[1,0,1]
	v_pk_fma_f32 v[82:83], v[74:75], s[36:37], v[82:83] op_sel_hi:[1,0,1]
	v_pk_fma_f32 v[84:85], v[76:77], s[36:37], v[84:85] op_sel_hi:[1,0,1]
	v_pk_fma_f32 v[86:87], v[78:79], s[36:37], v[86:87] op_sel_hi:[1,0,1]
	s_nop 0
	v_sub_f32_e32 v80, v80, v161
	v_sub_f32_e32 v81, v81, v161
	v_sub_f32_e32 v82, v82, v161
	v_sub_f32_e32 v83, v83, v161
	v_sub_f32_e32 v84, v84, v161
	v_sub_f32_e32 v85, v85, v161
	v_sub_f32_e32 v86, v86, v161
	v_sub_f32_e32 v87, v87, v161
	v_exp_f32_e32 v80, v80
	v_exp_f32_e32 v81, v81
	v_exp_f32_e32 v82, v82
	v_exp_f32_e32 v83, v83
	v_exp_f32_e32 v84, v84
	v_exp_f32_e32 v85, v85
	v_exp_f32_e32 v86, v86
	v_exp_f32_e32 v87, v87
	s_nop 0
	v_pk_fma_f32 v[88:89], v[56:57], s[36:37], v[88:89] op_sel_hi:[1,0,1]
	v_pk_fma_f32 v[90:91], v[58:59], s[36:37], v[90:91] op_sel_hi:[1,0,1]
	v_pk_fma_f32 v[92:93], v[60:61], s[36:37], v[92:93] op_sel_hi:[1,0,1]
	v_pk_fma_f32 v[94:95], v[62:63], s[36:37], v[94:95] op_sel_hi:[1,0,1]
	s_nop 0
	v_sub_f32_e32 v88, v88, v241
	v_sub_f32_e32 v89, v89, v241
	v_sub_f32_e32 v90, v90, v241
	v_sub_f32_e32 v91, v91, v241
	v_sub_f32_e32 v92, v92, v241
	v_sub_f32_e32 v93, v93, v241
	v_sub_f32_e32 v94, v94, v241
	v_sub_f32_e32 v95, v95, v241
	v_exp_f32_e32 v88, v88
	v_exp_f32_e32 v89, v89
	v_exp_f32_e32 v90, v90
	v_exp_f32_e32 v91, v91
	v_exp_f32_e32 v92, v92
	v_exp_f32_e32 v93, v93
	v_exp_f32_e32 v94, v94
	v_exp_f32_e32 v95, v95
	s_nop 0
	v_mov_b32_e32 v54, v81
	v_mov_b32_e32 v55, v83
	v_mov_b32_e32 v81, v82
	v_pk_mul_f32 v[54:55], v[34:35], v[54:55]
	s_nop 0
	v_pk_fma_f32 v[80:81], v[34:35], v[80:81], v[54:55]
	v_mov_b32_e32 v83, v55
	v_add_f32_e32 v72, v80, v81
	v_mov_b32_e32 v54, v85
	v_mov_b32_e32 v55, v87
	v_mov_b32_e32 v85, v86
	v_pk_mul_f32 v[54:55], v[34:35], v[54:55]
	s_nop 0
	v_pk_fma_f32 v[84:85], v[34:35], v[84:85], v[54:55]
	v_mov_b32_e32 v87, v55
	v_add_f32_e32 v73, v84, v85
	v_mov_b32_e32 v54, v89
	v_mov_b32_e32 v55, v91
	v_mov_b32_e32 v89, v90
	v_pk_mul_f32 v[54:55], v[36:37], v[54:55]
	s_nop 0
	v_pk_fma_f32 v[88:89], v[36:37], v[88:89], v[54:55]
	v_mov_b32_e32 v91, v55
	v_add_f32_e32 v74, v88, v89
	v_mov_b32_e32 v54, v93
	v_mov_b32_e32 v55, v95
	v_mov_b32_e32 v93, v94
	v_pk_mul_f32 v[54:55], v[36:37], v[54:55]
	s_nop 0
	v_pk_fma_f32 v[92:93], v[36:37], v[92:93], v[54:55]
	v_mov_b32_e32 v95, v55
	v_add_f32_e32 v75, v92, v93
	v_cndmask_b32_e64 v76, v83, v31, s[38:39]
	v_cndmask_b32_e64 v77, v87, v83, s[38:39]
	v_cndmask_b32_e64 v78, v91, v23, s[38:39]
	v_cndmask_b32_e64 v79, v95, v91, s[38:39]
	ds_bpermute_b32 v76, v0, v76
	ds_bpermute_b32 v77, v0, v77
	ds_bpermute_b32 v78, v0, v78
	ds_bpermute_b32 v79, v0, v79
	v_mov_b32_e32 v31, v87
	v_mov_b32_e32 v23, v95
	v_add_u32_e32 v54, 32, v49
	v_add_u32_e32 v55, 48, v49
	s_waitcnt lgkmcnt(0)
	v_add_f32_e32 v76, v72, v76
	v_add_f32_e32 v77, v73, v77
	v_add_f32_e32 v78, v74, v78
	v_add_f32_e32 v79, v75, v79
	v_xor_b32_e32 v54, v141, v54
	ds_write2st64_b32 v54, v76, v78 offset1:4
	v_xor_b32_e32 v55, v141, v55
	ds_write2st64_b32 v55, v77, v79 offset1:4
	s_branch .LBB0_365
.Lp2k_p0:
	ds_read_b128 v[56:59], v47
	ds_read_b128 v[64:67], v48
	ds_read_b128 v[60:63], v47 offset:2048
	ds_read_b128 v[68:71], v48 offset:2048
	v_subrev_u32_e32 v80, 31, v41
	v_subrev_u32_e32 v81, 47, v41
	v_subrev_u32_e32 v82, 63, v41
	v_subrev_u32_e32 v83, 79, v41
	v_min_u32_e32 v80, s31, v80
	v_min_u32_e32 v81, s31, v81
	v_min_u32_e32 v82, s31, v82
	v_min_u32_e32 v83, s31, v83
	v_xor_b32_e32 v80, s31, v80
	v_xor_b32_e32 v81, s31, v81
	v_xor_b32_e32 v82, s31, v82
	v_xor_b32_e32 v83, s31, v83
	v_lshl_add_u32 v80, v80, 2, v193
	v_lshl_add_u32 v81, v81, 2, v193
	v_lshl_add_u32 v82, v82, 2, v193
	v_lshl_add_u32 v83, v83, 2, v193
	v_subrev_u32_e32 v84, 287, v41
	v_subrev_u32_e32 v85, 303, v41
	v_subrev_u32_e32 v86, 319, v41
	v_subrev_u32_e32 v87, 335, v41
	v_min_u32_e32 v84, s31, v84
	v_min_u32_e32 v85, s31, v85
	v_min_u32_e32 v86, s31, v86
	v_min_u32_e32 v87, s31, v87
	v_xor_b32_e32 v84, s31, v84
	v_xor_b32_e32 v85, s31, v85
	v_xor_b32_e32 v86, s31, v86
	v_xor_b32_e32 v87, s31, v87
	v_lshl_add_u32 v84, v84, 2, v193
	v_lshl_add_u32 v85, v85, 2, v193
	v_lshl_add_u32 v86, v86, 2, v193
	v_lshl_add_u32 v87, v87, 2, v193
	v_subrev_u32_e32 v88, 27, v41
	v_subrev_u32_e32 v89, 43, v41
	v_subrev_u32_e32 v90, 59, v41
	v_subrev_u32_e32 v91, 75, v41
	v_min_u32_e32 v88, s31, v88
	v_min_u32_e32 v89, s31, v89
	v_min_u32_e32 v90, s31, v90
	v_min_u32_e32 v91, s31, v91
	v_xor_b32_e32 v88, s31, v88
	v_xor_b32_e32 v89, s31, v89
	v_xor_b32_e32 v90, s31, v90
	v_xor_b32_e32 v91, s31, v91
	v_lshl_add_u32 v88, v88, 2, v193
	v_lshl_add_u32 v89, v89, 2, v193
	v_lshl_add_u32 v90, v90, 2, v193
	v_lshl_add_u32 v91, v91, 2, v193
	v_subrev_u32_e32 v92, 283, v41
	v_subrev_u32_e32 v93, 299, v41
	v_subrev_u32_e32 v94, 315, v41
	v_subrev_u32_e32 v95, 331, v41
	v_min_u32_e32 v92, s31, v92
	v_min_u32_e32 v93, s31, v93
	v_min_u32_e32 v94, s31, v94
	v_min_u32_e32 v95, s31, v95
	v_xor_b32_e32 v92, s31, v92
	v_xor_b32_e32 v93, s31, v93
	v_xor_b32_e32 v94, s31, v94
	v_xor_b32_e32 v95, s31, v95
	v_lshl_add_u32 v92, v92, 2, v193
	v_lshl_add_u32 v93, v93, 2, v193
	v_lshl_add_u32 v94, v94, 2, v193
	v_lshl_add_u32 v95, v95, 2, v193
	ds_read_b32 v80, v80
	ds_read_b32 v81, v81
	ds_read_b32 v82, v82
	ds_read_b32 v83, v83
	ds_read_b32 v84, v84
	ds_read_b32 v85, v85
	ds_read_b32 v86, v86
	ds_read_b32 v87, v87
	s_waitcnt lgkmcnt(7)
	ds_read_b32 v88, v88
	ds_read_b32 v89, v89
	ds_read_b32 v90, v90
	ds_read_b32 v91, v91
	ds_read_b32 v92, v92
	ds_read_b32 v93, v93
	ds_read_b32 v94, v94
	ds_read_b32 v95, v95
	v_cmp_gt_u32_e64 s[12:13], s27, v46
	s_sub_i32 s98, s27, 16
	v_cmp_gt_u32_e64 s[6:7], s98, v46
	v_mfma_f32_16x16x32_bf16 v[72:75], v[56:59], v[2:5], 0
	v_mfma_f32_16x16x32_bf16 v[76:79], v[60:63], v[2:5], 0
	v_mfma_f32_16x16x32_bf16 v[72:75], v[64:67], v[6:9], v[72:75]
	v_mfma_f32_16x16x32_bf16 v[76:79], v[68:71], v[6:9], v[76:79]
	v_mfma_f32_16x16x32_bf16 v[56:59], v[56:59], v[10:13], 0
	v_mfma_f32_16x16x32_bf16 v[60:63], v[60:63], v[10:13], 0
	v_mfma_f32_16x16x32_bf16 v[56:59], v[64:67], v[14:17], v[56:59]
	v_mfma_f32_16x16x32_bf16 v[60:63], v[68:71], v[14:17], v[60:63]
	v_subrev_u32_e32 v96, 27, v41
	v_subrev_u32_e32 v97, 43, v41
	v_subrev_u32_e32 v98, 59, v41
	v_subrev_u32_e32 v99, 75, v41
	v_subrev_u32_e32 v100, 283, v41
	v_subrev_u32_e32 v101, 299, v41
	v_subrev_u32_e32 v54, 315, v41
	v_subrev_u32_e32 v55, 331, v41
	v_subrev_u32_e32 v64, 31, v41
	v_subrev_u32_e32 v65, 47, v41
	v_subrev_u32_e32 v66, 63, v41
	v_subrev_u32_e32 v67, 79, v41
	v_subrev_u32_e32 v68, 287, v41
	v_subrev_u32_e32 v69, 303, v41
	v_subrev_u32_e32 v70, 319, v41
	v_subrev_u32_e32 v71, 335, v41
	v_ashrrev_i32_e32 v96, 31, v96
	v_ashrrev_i32_e32 v97, 31, v97
	v_ashrrev_i32_e32 v98, 31, v98
	v_ashrrev_i32_e32 v99, 31, v99
	v_ashrrev_i32_e32 v100, 31, v100
	v_ashrrev_i32_e32 v101, 31, v101
	v_ashrrev_i32_e32 v54, 31, v54
	v_ashrrev_i32_e32 v55, 31, v55
	v_ashrrev_i32_e32 v64, 31, v64
	v_ashrrev_i32_e32 v65, 31, v65
	v_ashrrev_i32_e32 v66, 31, v66
	v_ashrrev_i32_e32 v67, 31, v67
	v_ashrrev_i32_e32 v68, 31, v68
	v_ashrrev_i32_e32 v69, 31, v69
	v_ashrrev_i32_e32 v70, 31, v70
	v_ashrrev_i32_e32 v71, 31, v71
	s_waitcnt lgkmcnt(0)
	v_fmac_f32_e32 v80, 0x3e38aa3b, v72
	v_fmac_f32_e32 v81, 0x3e38aa3b, v73
	v_fmac_f32_e32 v82, 0x3e38aa3b, v74
	v_fmac_f32_e32 v83, 0x3e38aa3b, v75
	v_fmac_f32_e32 v84, 0x3e38aa3b, v76
	v_fmac_f32_e32 v85, 0x3e38aa3b, v77
	v_fmac_f32_e32 v86, 0x3e38aa3b, v78
	v_fmac_f32_e32 v87, 0x3e38aa3b, v79
	v_sub_f32_e32 v80, v80, v161
	v_sub_f32_e32 v81, v81, v161
	v_sub_f32_e32 v82, v82, v161
	v_sub_f32_e32 v83, v83, v161
	v_sub_f32_e32 v84, v84, v161
	v_sub_f32_e32 v85, v85, v161
	v_sub_f32_e32 v86, v86, v161
	v_sub_f32_e32 v87, v87, v161
	v_exp_f32_e32 v80, v80
	v_exp_f32_e32 v81, v81
	v_exp_f32_e32 v82, v82
	v_exp_f32_e32 v83, v83
	v_exp_f32_e32 v84, v84
	v_exp_f32_e32 v85, v85
	v_exp_f32_e32 v86, v86
	v_exp_f32_e32 v87, v87
	s_nop 0
	v_fmac_f32_e32 v88, 0x3e38aa3b, v56
	v_fmac_f32_e32 v89, 0x3e38aa3b, v57
	v_fmac_f32_e32 v90, 0x3e38aa3b, v58
	v_fmac_f32_e32 v91, 0x3e38aa3b, v59
	v_fmac_f32_e32 v92, 0x3e38aa3b, v60
	v_fmac_f32_e32 v93, 0x3e38aa3b, v61
	v_fmac_f32_e32 v94, 0x3e38aa3b, v62
	v_fmac_f32_e32 v95, 0x3e38aa3b, v63
	v_sub_f32_e32 v88, v88, v241
	v_sub_f32_e32 v89, v89, v241
	v_sub_f32_e32 v90, v90, v241
	v_sub_f32_e32 v91, v91, v241
	v_sub_f32_e32 v92, v92, v241
	v_sub_f32_e32 v93, v93, v241
	v_sub_f32_e32 v94, v94, v241
	v_sub_f32_e32 v95, v95, v241
	v_exp_f32_e32 v88, v88
	v_exp_f32_e32 v89, v89
	v_exp_f32_e32 v90, v90
	v_exp_f32_e32 v91, v91
	v_exp_f32_e32 v92, v92
	v_exp_f32_e32 v93, v93
	v_exp_f32_e32 v94, v94
	v_exp_f32_e32 v95, v95
	s_nop 0
	v_mul_f32_e32 v80, v34, v80
	v_mul_f32_e32 v81, v34, v81
	v_mul_f32_e32 v82, v34, v82
	v_mul_f32_e32 v83, v34, v83
	v_bfi_b32 v80, v64, 0, v80
	v_bfi_b32 v81, v65, 0, v81
	v_bfi_b32 v82, v66, 0, v82
	v_bfi_b32 v83, v67, 0, v83
	v_cndmask_b32_e64 v83, 0, v83, s[12:13]
	v_add_f32_e32 v72, v80, v81
	v_add_f32_e32 v72, v72, v82
	v_add_f32_e32 v72, v72, v83
	v_mul_f32_e32 v84, v34, v84
	v_mul_f32_e32 v85, v34, v85
	v_mul_f32_e32 v86, v34, v86
	v_mul_f32_e32 v87, v34, v87
	v_bfi_b32 v84, v68, 0, v84
	v_bfi_b32 v85, v69, 0, v85
	v_bfi_b32 v86, v70, 0, v86
	v_bfi_b32 v87, v71, 0, v87
	v_cndmask_b32_e64 v87, 0, v87, s[6:7]
	v_add_f32_e32 v73, v84, v85
	v_add_f32_e32 v73, v73, v86
	v_add_f32_e32 v73, v73, v87
	v_mul_f32_e32 v88, v36, v88
	v_mul_f32_e32 v89, v36, v89
	v_mul_f32_e32 v90, v36, v90
	v_mul_f32_e32 v91, v36, v91
	v_bfi_b32 v88, v96, 0, v88
	v_bfi_b32 v89, v97, 0, v89
	v_bfi_b32 v90, v98, 0, v90
	v_bfi_b32 v91, v99, 0, v91
	v_cndmask_b32_e64 v91, 0, v91, s[12:13]
	v_add_f32_e32 v74, v88, v89
	v_add_f32_e32 v74, v74, v90
	v_add_f32_e32 v74, v74, v91
	v_mul_f32_e32 v92, v36, v92
	v_mul_f32_e32 v93, v36, v93
	v_mul_f32_e32 v94, v36, v94
	v_mul_f32_e32 v95, v36, v95
	v_bfi_b32 v92, v100, 0, v92
	v_bfi_b32 v93, v101, 0, v93
	v_bfi_b32 v94, v54, 0, v94
	v_bfi_b32 v95, v55, 0, v95
	v_cndmask_b32_e64 v95, 0, v95, s[6:7]
	v_add_f32_e32 v75, v92, v93
	v_add_f32_e32 v75, v75, v94
	v_add_f32_e32 v75, v75, v95
	v_cndmask_b32_e64 v76, v83, v31, s[38:39]
	v_cndmask_b32_e64 v77, v87, v83, s[38:39]
	v_cndmask_b32_e64 v78, v91, v23, s[38:39]
	v_cndmask_b32_e64 v79, v95, v91, s[38:39]
	ds_bpermute_b32 v76, v0, v76
	ds_bpermute_b32 v77, v0, v77
	ds_bpermute_b32 v78, v0, v78
	ds_bpermute_b32 v79, v0, v79
	v_mov_b32_e32 v31, v87
	v_mov_b32_e32 v23, v95
	v_mov_b32_e32 v54, v49
	v_add_u32_e32 v55, 16, v49
	s_waitcnt lgkmcnt(0)
	v_add_f32_e32 v76, v72, v76
	v_add_f32_e32 v77, v73, v77
	v_add_f32_e32 v78, v74, v78
	v_add_f32_e32 v79, v75, v79
	v_xor_b32_e32 v54, v141, v54
	ds_write2st64_b32 v54, v76, v78 offset1:4
	v_xor_b32_e32 v55, v141, v55
	ds_write2st64_b32 v55, v77, v79 offset1:4
	ds_read_b128 v[56:59], v47 offset:4096
	ds_read_b128 v[64:67], v48 offset:4096
	ds_read_b128 v[60:63], v47 offset:6144
	ds_read_b128 v[68:71], v48 offset:6144
	v_subrev_u32_e32 v80, 543, v41
	v_subrev_u32_e32 v81, 559, v41
	v_subrev_u32_e32 v82, 575, v41
	v_subrev_u32_e32 v83, 591, v41
	v_min_u32_e32 v80, s31, v80
	v_min_u32_e32 v81, s31, v81
	v_min_u32_e32 v82, s31, v82
	v_min_u32_e32 v83, s31, v83
	v_xor_b32_e32 v80, s31, v80
	v_xor_b32_e32 v81, s31, v81
	v_xor_b32_e32 v82, s31, v82
	v_xor_b32_e32 v83, s31, v83
	v_lshl_add_u32 v80, v80, 2, v193
	v_lshl_add_u32 v81, v81, 2, v193
	v_lshl_add_u32 v82, v82, 2, v193
	v_lshl_add_u32 v83, v83, 2, v193
	v_subrev_u32_e32 v84, 799, v41
	v_subrev_u32_e32 v85, 815, v41
	v_subrev_u32_e32 v86, 831, v41
	v_subrev_u32_e32 v87, 847, v41
	v_min_u32_e32 v84, s31, v84
	v_min_u32_e32 v85, s31, v85
	v_min_u32_e32 v86, s31, v86
	v_min_u32_e32 v87, s31, v87
	v_xor_b32_e32 v84, s31, v84
	v_xor_b32_e32 v85, s31, v85
	v_xor_b32_e32 v86, s31, v86
	v_xor_b32_e32 v87, s31, v87
	v_lshl_add_u32 v84, v84, 2, v193
	v_lshl_add_u32 v85, v85, 2, v193
	v_lshl_add_u32 v86, v86, 2, v193
	v_lshl_add_u32 v87, v87, 2, v193
	v_subrev_u32_e32 v88, 539, v41
	v_subrev_u32_e32 v89, 555, v41
	v_subrev_u32_e32 v90, 571, v41
	v_subrev_u32_e32 v91, 587, v41
	v_min_u32_e32 v88, s31, v88
	v_min_u32_e32 v89, s31, v89
	v_min_u32_e32 v90, s31, v90
	v_min_u32_e32 v91, s31, v91
	v_xor_b32_e32 v88, s31, v88
	v_xor_b32_e32 v89, s31, v89
	v_xor_b32_e32 v90, s31, v90
	v_xor_b32_e32 v91, s31, v91
	v_lshl_add_u32 v88, v88, 2, v193
	v_lshl_add_u32 v89, v89, 2, v193
	v_lshl_add_u32 v90, v90, 2, v193
	v_lshl_add_u32 v91, v91, 2, v193
	v_subrev_u32_e32 v92, 795, v41
	v_subrev_u32_e32 v93, 811, v41
	v_subrev_u32_e32 v94, 827, v41
	v_subrev_u32_e32 v95, 843, v41
	v_min_u32_e32 v92, s31, v92
	v_min_u32_e32 v93, s31, v93
	v_min_u32_e32 v94, s31, v94
	v_min_u32_e32 v95, s31, v95
	v_xor_b32_e32 v92, s31, v92
	v_xor_b32_e32 v93, s31, v93
	v_xor_b32_e32 v94, s31, v94
	v_xor_b32_e32 v95, s31, v95
	v_lshl_add_u32 v92, v92, 2, v193
	v_lshl_add_u32 v93, v93, 2, v193
	v_lshl_add_u32 v94, v94, 2, v193
	v_lshl_add_u32 v95, v95, 2, v193
	ds_read_b32 v80, v80
	ds_read_b32 v81, v81
	ds_read_b32 v82, v82
	ds_read_b32 v83, v83
	ds_read_b32 v84, v84
	ds_read_b32 v85, v85
	ds_read_b32 v86, v86
	ds_read_b32 v87, v87
	s_waitcnt lgkmcnt(7)
	ds_read_b32 v88, v88
	ds_read_b32 v89, v89
	ds_read_b32 v90, v90
	ds_read_b32 v91, v91
	ds_read_b32 v92, v92
	ds_read_b32 v93, v93
	ds_read_b32 v94, v94
	ds_read_b32 v95, v95
	s_sub_i32 s98, s27, 32
	v_cmp_gt_u32_e64 s[12:13], s98, v46
	s_sub_i32 s98, s27, 48
	v_cmp_gt_u32_e64 s[6:7], s98, v46
	v_mfma_f32_16x16x32_bf16 v[72:75], v[56:59], v[2:5], 0
	v_mfma_f32_16x16x32_bf16 v[76:79], v[60:63], v[2:5], 0
	v_mfma_f32_16x16x32_bf16 v[72:75], v[64:67], v[6:9], v[72:75]
	v_mfma_f32_16x16x32_bf16 v[76:79], v[68:71], v[6:9], v[76:79]
	v_mfma_f32_16x16x32_bf16 v[56:59], v[56:59], v[10:13], 0
	v_mfma_f32_16x16x32_bf16 v[60:63], v[60:63], v[10:13], 0
	v_mfma_f32_16x16x32_bf16 v[56:59], v[64:67], v[14:17], v[56:59]
	v_mfma_f32_16x16x32_bf16 v[60:63], v[68:71], v[14:17], v[60:63]
	v_subrev_u32_e32 v96, 539, v41
	v_subrev_u32_e32 v97, 555, v41
	v_subrev_u32_e32 v98, 571, v41
	v_subrev_u32_e32 v99, 587, v41
	v_subrev_u32_e32 v100, 795, v41
	v_subrev_u32_e32 v101, 811, v41
	v_subrev_u32_e32 v54, 827, v41
	v_subrev_u32_e32 v55, 843, v41
	v_subrev_u32_e32 v64, 543, v41
	v_subrev_u32_e32 v65, 559, v41
	v_subrev_u32_e32 v66, 575, v41
	v_subrev_u32_e32 v67, 591, v41
	v_subrev_u32_e32 v68, 799, v41
	v_subrev_u32_e32 v69, 815, v41
	v_subrev_u32_e32 v70, 831, v41
	v_subrev_u32_e32 v71, 847, v41
	v_ashrrev_i32_e32 v96, 31, v96
	v_ashrrev_i32_e32 v97, 31, v97
	v_ashrrev_i32_e32 v98, 31, v98
	v_ashrrev_i32_e32 v99, 31, v99
	v_ashrrev_i32_e32 v100, 31, v100
	v_ashrrev_i32_e32 v101, 31, v101
	v_ashrrev_i32_e32 v54, 31, v54
	v_ashrrev_i32_e32 v55, 31, v55
	v_ashrrev_i32_e32 v64, 31, v64
	v_ashrrev_i32_e32 v65, 31, v65
	v_ashrrev_i32_e32 v66, 31, v66
	v_ashrrev_i32_e32 v67, 31, v67
	v_ashrrev_i32_e32 v68, 31, v68
	v_ashrrev_i32_e32 v69, 31, v69
	v_ashrrev_i32_e32 v70, 31, v70
	v_ashrrev_i32_e32 v71, 31, v71
	s_waitcnt lgkmcnt(0)
	v_fmac_f32_e32 v80, 0x3e38aa3b, v72
	v_fmac_f32_e32 v81, 0x3e38aa3b, v73
	v_fmac_f32_e32 v82, 0x3e38aa3b, v74
	v_fmac_f32_e32 v83, 0x3e38aa3b, v75
	v_fmac_f32_e32 v84, 0x3e38aa3b, v76
	v_fmac_f32_e32 v85, 0x3e38aa3b, v77
	v_fmac_f32_e32 v86, 0x3e38aa3b, v78
	v_fmac_f32_e32 v87, 0x3e38aa3b, v79
	v_sub_f32_e32 v80, v80, v161
	v_sub_f32_e32 v81, v81, v161
	v_sub_f32_e32 v82, v82, v161
	v_sub_f32_e32 v83, v83, v161
	v_sub_f32_e32 v84, v84, v161
	v_sub_f32_e32 v85, v85, v161
	v_sub_f32_e32 v86, v86, v161
	v_sub_f32_e32 v87, v87, v161
	v_exp_f32_e32 v80, v80
	v_exp_f32_e32 v81, v81
	v_exp_f32_e32 v82, v82
	v_exp_f32_e32 v83, v83
	v_exp_f32_e32 v84, v84
	v_exp_f32_e32 v85, v85
	v_exp_f32_e32 v86, v86
	v_exp_f32_e32 v87, v87
	s_nop 0
	v_fmac_f32_e32 v88, 0x3e38aa3b, v56
	v_fmac_f32_e32 v89, 0x3e38aa3b, v57
	v_fmac_f32_e32 v90, 0x3e38aa3b, v58
	v_fmac_f32_e32 v91, 0x3e38aa3b, v59
	v_fmac_f32_e32 v92, 0x3e38aa3b, v60
	v_fmac_f32_e32 v93, 0x3e38aa3b, v61
	v_fmac_f32_e32 v94, 0x3e38aa3b, v62
	v_fmac_f32_e32 v95, 0x3e38aa3b, v63
	v_sub_f32_e32 v88, v88, v241
	v_sub_f32_e32 v89, v89, v241
	v_sub_f32_e32 v90, v90, v241
	v_sub_f32_e32 v91, v91, v241
	v_sub_f32_e32 v92, v92, v241
	v_sub_f32_e32 v93, v93, v241
	v_sub_f32_e32 v94, v94, v241
	v_sub_f32_e32 v95, v95, v241
	v_exp_f32_e32 v88, v88
	v_exp_f32_e32 v89, v89
	v_exp_f32_e32 v90, v90
	v_exp_f32_e32 v91, v91
	v_exp_f32_e32 v92, v92
	v_exp_f32_e32 v93, v93
	v_exp_f32_e32 v94, v94
	v_exp_f32_e32 v95, v95
	s_nop 0
	v_mul_f32_e32 v80, v34, v80
	v_mul_f32_e32 v81, v34, v81
	v_mul_f32_e32 v82, v34, v82
	v_mul_f32_e32 v83, v34, v83
	v_bfi_b32 v80, v64, 0, v80
	v_bfi_b32 v81, v65, 0, v81
	v_bfi_b32 v82, v66, 0, v82
	v_bfi_b32 v83, v67, 0, v83
	v_cndmask_b32_e64 v83, 0, v83, s[12:13]
	v_add_f32_e32 v72, v80, v81
	v_add_f32_e32 v72, v72, v82
	v_add_f32_e32 v72, v72, v83
	v_mul_f32_e32 v84, v34, v84
	v_mul_f32_e32 v85, v34, v85
	v_mul_f32_e32 v86, v34, v86
	v_mul_f32_e32 v87, v34, v87
	v_bfi_b32 v84, v68, 0, v84
	v_bfi_b32 v85, v69, 0, v85
	v_bfi_b32 v86, v70, 0, v86
	v_bfi_b32 v87, v71, 0, v87
	v_cndmask_b32_e64 v87, 0, v87, s[6:7]
	v_add_f32_e32 v73, v84, v85
	v_add_f32_e32 v73, v73, v86
	v_add_f32_e32 v73, v73, v87
	v_mul_f32_e32 v88, v36, v88
	v_mul_f32_e32 v89, v36, v89
	v_mul_f32_e32 v90, v36, v90
	v_mul_f32_e32 v91, v36, v91
	v_bfi_b32 v88, v96, 0, v88
	v_bfi_b32 v89, v97, 0, v89
	v_bfi_b32 v90, v98, 0, v90
	v_bfi_b32 v91, v99, 0, v91
	v_cndmask_b32_e64 v91, 0, v91, s[12:13]
	v_add_f32_e32 v74, v88, v89
	v_add_f32_e32 v74, v74, v90
	v_add_f32_e32 v74, v74, v91
	v_mul_f32_e32 v92, v36, v92
	v_mul_f32_e32 v93, v36, v93
	v_mul_f32_e32 v94, v36, v94
	v_mul_f32_e32 v95, v36, v95
	v_bfi_b32 v92, v100, 0, v92
	v_bfi_b32 v93, v101, 0, v93
	v_bfi_b32 v94, v54, 0, v94
	v_bfi_b32 v95, v55, 0, v95
	v_cndmask_b32_e64 v95, 0, v95, s[6:7]
	v_add_f32_e32 v75, v92, v93
	v_add_f32_e32 v75, v75, v94
	v_add_f32_e32 v75, v75, v95
	v_cndmask_b32_e64 v76, v83, v31, s[38:39]
	v_cndmask_b32_e64 v77, v87, v83, s[38:39]
	v_cndmask_b32_e64 v78, v91, v23, s[38:39]
	v_cndmask_b32_e64 v79, v95, v91, s[38:39]
	ds_bpermute_b32 v76, v0, v76
	ds_bpermute_b32 v77, v0, v77
	ds_bpermute_b32 v78, v0, v78
	ds_bpermute_b32 v79, v0, v79
	v_mov_b32_e32 v31, v87
	v_mov_b32_e32 v23, v95
	v_add_u32_e32 v54, 32, v49
	v_add_u32_e32 v55, 48, v49
	s_waitcnt lgkmcnt(0)
	v_add_f32_e32 v76, v72, v76
	v_add_f32_e32 v77, v73, v77
	v_add_f32_e32 v78, v74, v78
	v_add_f32_e32 v79, v75, v79
	v_xor_b32_e32 v54, v141, v54
	ds_write2st64_b32 v54, v76, v78 offset1:4
	v_xor_b32_e32 v55, v141, v55
	ds_write2st64_b32 v55, v77, v79 offset1:4
	s_branch .LBB0_365
.Lp2k_inv:
	v_cndmask_b32_e64 v72, 0, v31, s[38:39]
	v_cndmask_b32_e64 v73, 0, v23, s[38:39]
	ds_bpermute_b32 v72, v0, v72
	ds_bpermute_b32 v73, v0, v73
	v_mov_b32_e32 v74, 0
	v_mov_b32_e32 v31, 0
	v_mov_b32_e32 v23, 0
	v_add_u32_e32 v54, 16, v49
	v_add_u32_e32 v55, 32, v49
	v_add_u32_e32 v56, 48, v49
	s_waitcnt lgkmcnt(0)
	v_add_f32_e32 v72, 0, v72
	v_add_f32_e32 v73, 0, v73
	v_xor_b32_e32 v57, v141, v49
	ds_write2st64_b32 v57, v72, v73 offset1:4
	v_xor_b32_e32 v54, v141, v54
	ds_write2st64_b32 v54, v74, v74 offset1:4
	v_xor_b32_e32 v55, v141, v55
	ds_write2st64_b32 v55, v74, v74 offset1:4
	v_xor_b32_e32 v56, v141, v56
	ds_write2st64_b32 v56, v74, v74 offset1:4
	s_branch .LBB0_365

.LBB0_404:
	s_lshr_b32 s10, s0, 3
	s_and_b32 s10, s10, 3
	s_lshl_b32 s10, s10, 6
	v_xor_b32_e32 v20, s10, v0
	v_xor_b32_e32 v21, 16, v20
	v_xor_b32_e32 v22, 32, v20
	v_xor_b32_e32 v23, 48, v20
	ds_read_b32 v18, v20
	ds_read_b32 v19, v21 offset:16384
	ds_read_b32 v24, v22 offset:32768
	ds_read_b32 v25, v23 offset:49152
	s_mov_b64 s[22:23], s[8:9]
	s_waitcnt lgkmcnt(0)
	v_add_f32_e32 v20, v18, v19
	v_add_f32_e32 v18, v20, v24
	v_add_f32_e32 v18, v18, v25
	v_add_f32_e32 v19, 0x49742400, v18
	v_cndmask_b32_e32 v18, v18, v19, vcc
	v_cndmask_b32_e64 v18, v18, v148, s[42:43]
	v_not_b32_e32 v19, v18
	v_cmp_gt_i32_e64 s[6:7], 0, v18
	s_nop 1
	v_cndmask_b32_e64 v18, -|v18|, v19, s[6:7]
	v_cmp_gt_i32_e64 s[6:7], 0, v18
	s_bcnt1_i32_b64 s16, s[6:7]
	s_cmp_gt_u32 s16, 15
	s_cselect_b32 s10, 0x80000000, 0
	s_or_b32 s11, s10, 2.0
	v_cmp_le_u32_e64 s[6:7], s11, v18
	s_bcnt1_i32_b64 s16, s[6:7]
	s_cmp_gt_u32 s16, 15
	s_cselect_b32 s10, s11, s10
	s_or_b32 s11, s10, 0x20000000
	v_cmp_le_u32_e64 s[6:7], s11, v18
	s_bcnt1_i32_b64 s16, s[6:7]
	s_cmp_gt_u32 s16, 15
	s_cselect_b32 s10, s11, s10
	s_or_b32 s11, s10, 0x10000000
	v_cmp_le_u32_e64 s[6:7], s11, v18
	s_bcnt1_i32_b64 s16, s[6:7]
	s_cmp_gt_u32 s16, 15
	s_cselect_b32 s10, s11, s10
	s_or_b32 s11, s10, 0x8000000
	v_cmp_le_u32_e64 s[6:7], s11, v18
	s_bcnt1_i32_b64 s16, s[6:7]
	s_cmp_gt_u32 s16, 15
	s_cselect_b32 s10, s11, s10
	s_or_b32 s11, s10, 0x4000000
	v_cmp_le_u32_e64 s[6:7], s11, v18
	s_bcnt1_i32_b64 s16, s[6:7]
	s_cmp_gt_u32 s16, 15
	s_cselect_b32 s10, s11, s10
	s_or_b32 s11, s10, 0x2000000
	v_cmp_le_u32_e64 s[6:7], s11, v18
	s_bcnt1_i32_b64 s16, s[6:7]
	s_cmp_gt_u32 s16, 15
	s_cselect_b32 s10, s11, s10
	s_or_b32 s11, s10, 0x1000000
	v_cmp_le_u32_e64 s[6:7], s11, v18
	s_bcnt1_i32_b64 s16, s[6:7]
	s_cmp_gt_u32 s16, 15
	s_cselect_b32 s10, s11, s10
	s_or_b32 s11, s10, 0x800000
	v_cmp_le_u32_e64 s[6:7], s11, v18
	s_bcnt1_i32_b64 s16, s[6:7]
	s_cmp_gt_u32 s16, 15
	s_cselect_b32 s10, s11, s10
	s_or_b32 s11, s10, 0x400000
	v_cmp_le_u32_e64 s[6:7], s11, v18
	s_bcnt1_i32_b64 s16, s[6:7]
	s_cmp_gt_u32 s16, 15
	s_cselect_b32 s10, s11, s10
	s_or_b32 s11, s10, 0x200000
	v_cmp_le_u32_e64 s[6:7], s11, v18
	s_bcnt1_i32_b64 s16, s[6:7]
	s_cmp_gt_u32 s16, 15
	s_cselect_b32 s10, s11, s10
	s_or_b32 s11, s10, 0x100000
	v_cmp_le_u32_e64 s[6:7], s11, v18
	s_bcnt1_i32_b64 s16, s[6:7]
	s_cmp_gt_u32 s16, 15
	s_cselect_b32 s10, s11, s10
	s_or_b32 s11, s10, 0x80000
	v_cmp_le_u32_e64 s[6:7], s11, v18
	s_bcnt1_i32_b64 s16, s[6:7]
	s_cmp_gt_u32 s16, 15
	s_cselect_b32 s10, s11, s10
	s_or_b32 s11, s10, 0x40000
	v_cmp_le_u32_e64 s[6:7], s11, v18
	s_bcnt1_i32_b64 s16, s[6:7]
	s_cmp_gt_u32 s16, 15
	s_cselect_b32 s10, s11, s10
	s_or_b32 s11, s10, 0x20000
	v_cmp_le_u32_e64 s[6:7], s11, v18
	s_bcnt1_i32_b64 s16, s[6:7]
	s_cmp_gt_u32 s16, 15
	s_cselect_b32 s10, s11, s10
	s_or_b32 s11, s10, 0x10000
	v_cmp_le_u32_e64 s[6:7], s11, v18
	s_bcnt1_i32_b64 s16, s[6:7]
	s_cmp_gt_u32 s16, 15
	s_cselect_b32 s10, s11, s10
	s_or_b32 s11, s10, 0x8000
	v_cmp_le_u32_e64 s[6:7], s11, v18
	s_bcnt1_i32_b64 s16, s[6:7]
	s_cmp_gt_u32 s16, 15
	s_cselect_b32 s10, s11, s10
	s_or_b32 s11, s10, 0x4000
	v_cmp_le_u32_e64 s[6:7], s11, v18
	s_bcnt1_i32_b64 s16, s[6:7]
	s_cmp_gt_u32 s16, 15
	s_cselect_b32 s10, s11, s10
	s_or_b32 s11, s10, 0x2000
	v_cmp_le_u32_e64 s[6:7], s11, v18
	s_bcnt1_i32_b64 s16, s[6:7]
	s_cmp_gt_u32 s16, 15
	s_cselect_b32 s10, s11, s10
	s_or_b32 s11, s10, 0x1000
	v_cmp_le_u32_e64 s[6:7], s11, v18
	s_bcnt1_i32_b64 s16, s[6:7]
	s_cmp_gt_u32 s16, 15
	s_cselect_b32 s10, s11, s10
	s_or_b32 s11, s10, 0x800
	v_cmp_le_u32_e64 s[6:7], s11, v18
	s_bcnt1_i32_b64 s16, s[6:7]
	s_cmp_gt_u32 s16, 15
	s_cselect_b32 s10, s11, s10
	s_or_b32 s11, s10, 0x400
	v_cmp_le_u32_e64 s[6:7], s11, v18
	s_bcnt1_i32_b64 s16, s[6:7]
	s_cmp_gt_u32 s16, 15
	s_cselect_b32 s10, s11, s10
	s_or_b32 s11, s10, 0x200
	v_cmp_le_u32_e64 s[6:7], s11, v18
	s_bcnt1_i32_b64 s16, s[6:7]
	s_cmp_gt_u32 s16, 15
	s_cselect_b32 s10, s11, s10
	s_or_b32 s11, s10, 0x100
	v_cmp_le_u32_e64 s[6:7], s11, v18
	s_bcnt1_i32_b64 s16, s[6:7]
	s_cmp_gt_u32 s16, 15
	s_cselect_b32 s10, s11, s10
	s_or_b32 s11, s10, 0x80
	v_cmp_le_u32_e64 s[6:7], s11, v18
	s_bcnt1_i32_b64 s16, s[6:7]
	s_cmp_gt_u32 s16, 15
	s_cselect_b32 s10, s11, s10
	s_or_b32 s11, s10, 64
	v_cmp_le_u32_e64 s[6:7], s11, v18
	s_bcnt1_i32_b64 s16, s[6:7]
	s_cmp_gt_u32 s16, 15
	s_cselect_b32 s10, s11, s10
	s_or_b32 s11, s10, 32
	v_cmp_le_u32_e64 s[6:7], s11, v18
	s_bcnt1_i32_b64 s16, s[6:7]
	s_cmp_gt_u32 s16, 15
	s_cselect_b32 s10, s11, s10
	s_or_b32 s11, s10, 16
	v_cmp_le_u32_e64 s[6:7], s11, v18
	s_bcnt1_i32_b64 s16, s[6:7]
	s_cmp_gt_u32 s16, 15
	s_cselect_b32 s10, s11, s10
	s_or_b32 s11, s10, 8
	v_cmp_le_u32_e64 s[6:7], s11, v18
	s_bcnt1_i32_b64 s16, s[6:7]
	s_cmp_gt_u32 s16, 15
	s_cselect_b32 s10, s11, s10
	s_or_b32 s11, s10, 4
	v_cmp_le_u32_e64 s[6:7], s11, v18
	s_bcnt1_i32_b64 s16, s[6:7]
	s_cmp_gt_u32 s16, 15
	s_cselect_b32 s10, s11, s10
	s_or_b32 s11, s10, 2
	v_cmp_le_u32_e64 s[6:7], s11, v18
	s_bcnt1_i32_b64 s16, s[6:7]
	s_cmp_gt_u32 s16, 15
	s_cselect_b32 s10, s11, s10
	s_or_b32 s11, s10, 1
	v_cmp_le_u32_e64 s[6:7], s11, v18
	s_bcnt1_i32_b64 s16, s[6:7]
	s_cmp_gt_u32 s16, 15
	s_cselect_b32 s4, s11, s10
	v_cmp_eq_u32_e64 s[44:45], s4, v18
	v_cmp_ge_u32_e64 s[6:7], s4, v18
	v_cmp_lt_u32_e64 s[46:47], s4, v18
	s_and_saveexec_b64 s[10:11], s[6:7]
	s_cbranch_execz .LBB0_406
	s_bcnt1_i32_b64 s4, s[46:47]
	v_mbcnt_lo_u32_b32 v18, s44, 0
	s_sub_i32 s4, 16, s4
	v_mbcnt_hi_u32_b32 v18, s45, v18
	v_cmp_gt_i32_e64 s[6:7], s4, v18
	s_and_b64 s[4:5], s[44:45], s[6:7]
	s_and_b64 s[4:5], s[4:5], s[8:9]
	s_andn2_b64 s[6:7], s[8:9], exec
	s_and_b64 s[4:5], s[4:5], exec
	s_or_b64 s[22:23], s[6:7], s[4:5]
